# readout1 epilogue: residual rows and the 4 distinct gate quads loaded in two batches of 8 blocks instead of 16 serial load/wait/store round trips
# baseline (speedup 1.0000x reference)
.LBB0_1215:
	v_add_u32_e32 v112, s40, v156
	v_add_u32_e32 v116, s39, v157
	v_ashrrev_i32_e32 v113, 31, v112
	v_lshrrev_b32_e32 v114, 20, v113
	v_add_u32_e32 v114, v112, v114
	v_ashrrev_i32_e32 v114, 12, v114
	v_add_u32_e32 v114, s36, v114
	v_mul_hi_i32_i24_e32 v115, 0x3000, v114
	v_mul_i32_i24_e32 v114, 0x3000, v114
	v_lshlrev_b64 v[118:119], 12, v[112:113]
	v_lshl_add_u64 v[114:115], s[60:61], 0, v[114:115]
	v_ashrrev_i32_e32 v117, 31, v116
	v_lshl_add_u64 v[114:115], v[114:115], 0, s[58:59]
	v_lshlrev_b64 v[116:117], 2, v[116:117]
	v_lshl_add_u64 v[118:119], s[16:17], 0, v[118:119]
	v_lshl_add_u64 v[114:115], v[114:115], 0, v[116:117]
	v_lshl_add_u64 v[118:119], v[118:119], 0, v[116:117]
	global_load_dwordx4 v[64:67], v[114:115], off
	global_load_dwordx4 v[68:71], v[114:115], off offset:64
	global_load_dwordx4 v[72:75], v[114:115], off offset:128
	global_load_dwordx4 v[76:79], v[114:115], off offset:192
	v_add_co_u32_e32 v120, vcc, 0x10000, v118
	s_mov_b32 s52, s38
	v_addc_co_u32_e32 v121, vcc, 0, v119, vcc
	s_mov_b32 s39, s37
	s_mov_b32 s40, s24
	global_load_dwordx4 v[80:83], v[118:119], off
	global_load_dwordx4 v[84:87], v[118:119], off offset:64
	global_load_dwordx4 v[88:91], v[118:119], off offset:128
	global_load_dwordx4 v[92:95], v[118:119], off offset:192
	global_load_dwordx4 v[96:99], v[120:121], off
	global_load_dwordx4 v[100:103], v[120:121], off offset:64
	global_load_dwordx4 v[104:107], v[120:121], off offset:128
	global_load_dwordx4 v[108:111], v[120:121], off offset:192
	v_add_co_u32_e32 v122, vcc, 0x20000, v118
	s_nop 0
	v_addc_co_u32_e32 v123, vcc, 0, v119, vcc
	v_add_co_u32_e32 v124, vcc, 0x30000, v118
	s_nop 0
	v_addc_co_u32_e32 v125, vcc, 0, v119, vcc
	s_waitcnt vmcnt(0)
	v_pk_fma_f32 v[62:63], v[62:63], v[66:67], v[82:83]
	v_pk_fma_f32 v[60:61], v[60:61], v[64:65], v[80:81]
	v_pk_fma_f32 v[58:59], v[58:59], v[70:71], v[86:87]
	v_pk_fma_f32 v[56:57], v[56:57], v[68:69], v[84:85]
	v_pk_fma_f32 v[54:55], v[54:55], v[74:75], v[90:91]
	v_pk_fma_f32 v[52:53], v[52:53], v[72:73], v[88:89]
	v_pk_fma_f32 v[50:51], v[50:51], v[78:79], v[94:95]
	v_pk_fma_f32 v[48:49], v[48:49], v[76:77], v[92:93]
	v_pk_fma_f32 v[46:47], v[46:47], v[66:67], v[98:99]
	v_pk_fma_f32 v[44:45], v[44:45], v[64:65], v[96:97]
	v_pk_fma_f32 v[42:43], v[42:43], v[70:71], v[102:103]
	v_pk_fma_f32 v[40:41], v[40:41], v[68:69], v[100:101]
	v_pk_fma_f32 v[38:39], v[38:39], v[74:75], v[106:107]
	v_pk_fma_f32 v[36:37], v[36:37], v[72:73], v[104:105]
	v_pk_fma_f32 v[34:35], v[34:35], v[78:79], v[110:111]
	v_pk_fma_f32 v[32:33], v[32:33], v[76:77], v[108:109]
	global_load_dwordx4 v[80:83], v[122:123], off
	global_load_dwordx4 v[84:87], v[122:123], off offset:64
	global_load_dwordx4 v[88:91], v[122:123], off offset:128
	global_load_dwordx4 v[92:95], v[122:123], off offset:192
	global_load_dwordx4 v[96:99], v[124:125], off
	global_load_dwordx4 v[100:103], v[124:125], off offset:64
	global_load_dwordx4 v[104:107], v[124:125], off offset:128
	global_load_dwordx4 v[108:111], v[124:125], off offset:192
	global_store_dwordx4 v[118:119], v[60:63], off
	global_store_dwordx4 v[118:119], v[56:59], off offset:64
	global_store_dwordx4 v[118:119], v[52:55], off offset:128
	global_store_dwordx4 v[118:119], v[48:51], off offset:192
	global_store_dwordx4 v[120:121], v[44:47], off
	global_store_dwordx4 v[120:121], v[40:43], off offset:64
	global_store_dwordx4 v[120:121], v[36:39], off offset:128
	global_store_dwordx4 v[120:121], v[32:35], off offset:192
	s_waitcnt vmcnt(8)
	v_pk_fma_f32 v[30:31], v[30:31], v[66:67], v[82:83]
	v_pk_fma_f32 v[28:29], v[28:29], v[64:65], v[80:81]
	v_pk_fma_f32 v[26:27], v[26:27], v[70:71], v[86:87]
	v_pk_fma_f32 v[24:25], v[24:25], v[68:69], v[84:85]
	v_pk_fma_f32 v[22:23], v[22:23], v[74:75], v[90:91]
	v_pk_fma_f32 v[20:21], v[20:21], v[72:73], v[88:89]
	v_pk_fma_f32 v[18:19], v[18:19], v[78:79], v[94:95]
	v_pk_fma_f32 v[16:17], v[16:17], v[76:77], v[92:93]
	v_pk_fma_f32 v[14:15], v[14:15], v[66:67], v[98:99]
	v_pk_fma_f32 v[12:13], v[12:13], v[64:65], v[96:97]
	v_pk_fma_f32 v[10:11], v[10:11], v[70:71], v[102:103]
	v_pk_fma_f32 v[8:9], v[8:9], v[68:69], v[100:101]
	v_pk_fma_f32 v[2:3], v[2:3], v[74:75], v[106:107]
	v_pk_fma_f32 v[0:1], v[0:1], v[72:73], v[104:105]
	v_pk_fma_f32 v[6:7], v[6:7], v[78:79], v[110:111]
	v_pk_fma_f32 v[4:5], v[4:5], v[76:77], v[108:109]
	global_store_dwordx4 v[122:123], v[28:31], off
	global_store_dwordx4 v[122:123], v[24:27], off offset:64
	global_store_dwordx4 v[122:123], v[20:23], off offset:128
	global_store_dwordx4 v[122:123], v[16:19], off offset:192
	global_store_dwordx4 v[124:125], v[12:15], off
	global_store_dwordx4 v[124:125], v[8:11], off offset:64
	global_store_dwordx4 v[124:125], v[0:3], off offset:128
	global_store_dwordx4 v[124:125], v[4:7], off offset:192
	s_andn2_b64 vcc, exec, s[34:35]
	s_cbranch_vccz .LBB0_1235
